# fused-norm publish: the 8 per-row sum reductions batched in three stages (was 8 serialized bpermute-wait chains), both exchanges
# speedup vs baseline: 1.0276x; 1.0095x over previous
; __device__ __forceinline__ float shx(float v, int o, int lane) { return __builtin_bit_cast(float, __builtin_amdgcn_ds_bpermute((lane ^ o) << 2, __builtin_bit_cast(int, v))); }
; #define PG8_LAS __attribute__((address_space(3)))
; __device__ __forceinline__ void panel_ss_publish(const f32x4 (&v)[2][2][4][2], const Unit& u, int wr, int wc, int fr, int fq, PG8_LAS unsigned char* lds, int wid, int lane, float* slots, unsigned* cnt) {
;     PG8_LAS float* P = (PG8_LAS float*)lds;
; #pragma unroll
;     for (int ai = 0; ai < 2; ++ai)
; #pragma unroll
;         for (int m = 0; m < 4; ++m) { float s = 0.f;
; #pragma unroll
;             for (int bj = 0; bj < 2; ++bj)
; #pragma unroll
;                 for (int n = 0; n < 2; ++n) { const f32x4 x = v[ai][bj][m][n]; s += (x[0] * x[0] + x[1] * x[1]) + (x[2] * x[2] + x[3] * x[3]); }
;             s += shx(s, 16, lane); s += shx(s, 32, lane);
;             if (fq == 0) P[(ai * HALF + wr * 64 + m * 16 + fr) * 4 + wc] = s; }
.LBB0_146:
	s_waitcnt vmcnt(0)
	v_readlane_b32 s0, v255, 20
	v_readlane_b32 s1, v255, 21
	v_readlane_b32 s42, v255, 30
	s_andn2_b64 vcc, exec, s[0:1]
	v_readlane_b32 s17, v255, 11
	v_readlane_b32 s43, v255, 31
	s_barrier
	s_cbranch_vccnz .LBB0_274
	v_and_b32_e32 v239, 63, v236
	v_lshlrev_b32_e32 v0, 2, v239
	v_xor_b32_e32 v240, 64, v0
	v_xor_b32_e32 v241, 0x80, v0
	s_lshl_b32 s0, s64, 2
	v_cmp_gt_u32_e64 s[6:7], 16, v239
	s_add_i32 s36, s0, 0
	s_lshl_b32 s2, s57, 10
	s_add_i32 s2, s36, s2
	v_mul_f32_e32 v132, v127, v127
	v_mul_f32_e32 v131, v129, v129
	v_fmac_f32_e32 v132, v126, v126
	v_fmac_f32_e32 v131, v128, v128
	v_add_f32_e32 v132, v132, v131
	v_mul_f32_e32 v130, v123, v123
	v_mul_f32_e32 v131, v125, v125
	v_fmac_f32_e32 v130, v122, v122
	v_fmac_f32_e32 v131, v124, v124
	v_add_f32_e32 v130, v130, v131
	v_add_f32_e32 v132, v130, v132
	v_mul_f32_e32 v130, v119, v119
	v_mul_f32_e32 v131, v121, v121
	v_fmac_f32_e32 v130, v118, v118
	v_fmac_f32_e32 v131, v120, v120
	v_add_f32_e32 v130, v130, v131
	v_add_f32_e32 v132, v130, v132
	v_mul_f32_e32 v130, v115, v115
	v_mul_f32_e32 v131, v117, v117
	v_fmac_f32_e32 v130, v114, v114
	v_fmac_f32_e32 v131, v116, v116
	v_add_f32_e32 v130, v130, v131
	v_add_f32_e32 v132, v130, v132
	ds_bpermute_b32 v140, v240, v132
	v_mul_f32_e32 v133, v111, v111
	v_mul_f32_e32 v131, v113, v113
	v_fmac_f32_e32 v133, v110, v110
	v_fmac_f32_e32 v131, v112, v112
	v_add_f32_e32 v133, v133, v131
	v_mul_f32_e32 v130, v107, v107
	v_mul_f32_e32 v131, v109, v109
	v_fmac_f32_e32 v130, v106, v106
	v_fmac_f32_e32 v131, v108, v108
	v_add_f32_e32 v130, v130, v131
	v_add_f32_e32 v133, v130, v133
	v_mul_f32_e32 v130, v103, v103
	v_mul_f32_e32 v131, v105, v105
	v_fmac_f32_e32 v130, v102, v102
	v_fmac_f32_e32 v131, v104, v104
	v_add_f32_e32 v130, v130, v131
	v_add_f32_e32 v133, v130, v133
	v_mul_f32_e32 v130, v99, v99
	v_mul_f32_e32 v131, v101, v101
	v_fmac_f32_e32 v130, v98, v98
	v_fmac_f32_e32 v131, v100, v100
	v_add_f32_e32 v130, v130, v131
	v_add_f32_e32 v133, v130, v133
	ds_bpermute_b32 v141, v240, v133
	v_mul_f32_e32 v134, v95, v95
	v_mul_f32_e32 v131, v97, v97
	v_fmac_f32_e32 v134, v94, v94
	v_fmac_f32_e32 v131, v96, v96
	v_add_f32_e32 v134, v134, v131
	v_mul_f32_e32 v130, v91, v91
	v_mul_f32_e32 v131, v93, v93
	v_fmac_f32_e32 v130, v90, v90
	v_fmac_f32_e32 v131, v92, v92
	v_add_f32_e32 v130, v130, v131
	v_add_f32_e32 v134, v130, v134
	v_mul_f32_e32 v130, v87, v87
	v_mul_f32_e32 v131, v89, v89
	v_fmac_f32_e32 v130, v86, v86
	v_fmac_f32_e32 v131, v88, v88
	v_add_f32_e32 v130, v130, v131
	v_add_f32_e32 v134, v130, v134
	v_mul_f32_e32 v130, v83, v83
	v_mul_f32_e32 v131, v85, v85
	v_fmac_f32_e32 v130, v82, v82
	v_fmac_f32_e32 v131, v84, v84
	v_add_f32_e32 v130, v130, v131
	v_add_f32_e32 v134, v130, v134
	ds_bpermute_b32 v142, v240, v134
	v_mul_f32_e32 v135, v79, v79
	v_mul_f32_e32 v131, v81, v81
	v_fmac_f32_e32 v135, v78, v78
	v_fmac_f32_e32 v131, v80, v80
	v_add_f32_e32 v135, v135, v131
	v_mul_f32_e32 v130, v75, v75
	v_mul_f32_e32 v131, v77, v77
	v_fmac_f32_e32 v130, v74, v74
	v_fmac_f32_e32 v131, v76, v76
	v_add_f32_e32 v130, v130, v131
	v_add_f32_e32 v135, v130, v135
	v_mul_f32_e32 v130, v71, v71
	v_mul_f32_e32 v131, v73, v73
	v_fmac_f32_e32 v130, v70, v70
	v_fmac_f32_e32 v131, v72, v72
	v_add_f32_e32 v130, v130, v131
	v_add_f32_e32 v135, v130, v135
	v_mul_f32_e32 v130, v67, v67
	v_mul_f32_e32 v131, v69, v69
	v_fmac_f32_e32 v130, v66, v66
	v_fmac_f32_e32 v131, v68, v68
	v_add_f32_e32 v130, v130, v131
	v_add_f32_e32 v135, v130, v135
	ds_bpermute_b32 v143, v240, v135
	v_mul_f32_e32 v136, v63, v63
	v_mul_f32_e32 v131, v65, v65
	v_fmac_f32_e32 v136, v62, v62
	v_fmac_f32_e32 v131, v64, v64
	v_add_f32_e32 v136, v136, v131
	v_mul_f32_e32 v130, v59, v59
	v_mul_f32_e32 v131, v61, v61
	v_fmac_f32_e32 v130, v58, v58
	v_fmac_f32_e32 v131, v60, v60
	v_add_f32_e32 v130, v130, v131
	v_add_f32_e32 v136, v130, v136
	v_mul_f32_e32 v130, v55, v55
	v_mul_f32_e32 v131, v57, v57
	v_fmac_f32_e32 v130, v54, v54
	v_fmac_f32_e32 v131, v56, v56
	v_add_f32_e32 v130, v130, v131
	v_add_f32_e32 v136, v130, v136
	v_mul_f32_e32 v130, v51, v51
	v_mul_f32_e32 v131, v53, v53
	v_fmac_f32_e32 v130, v50, v50
	v_fmac_f32_e32 v131, v52, v52
	v_add_f32_e32 v130, v130, v131
	v_add_f32_e32 v136, v130, v136
	ds_bpermute_b32 v144, v240, v136
	v_mul_f32_e32 v137, v47, v47
	v_mul_f32_e32 v131, v49, v49
	v_fmac_f32_e32 v137, v46, v46
	v_fmac_f32_e32 v131, v48, v48
	v_add_f32_e32 v137, v137, v131
	v_mul_f32_e32 v130, v43, v43
	v_mul_f32_e32 v131, v45, v45
	v_fmac_f32_e32 v130, v42, v42
	v_fmac_f32_e32 v131, v44, v44
	v_add_f32_e32 v130, v130, v131
	v_add_f32_e32 v137, v130, v137
	v_mul_f32_e32 v130, v39, v39
	v_mul_f32_e32 v131, v41, v41
	v_fmac_f32_e32 v130, v38, v38
	v_fmac_f32_e32 v131, v40, v40
	v_add_f32_e32 v130, v130, v131
	v_add_f32_e32 v137, v130, v137
	v_mul_f32_e32 v130, v35, v35
	v_mul_f32_e32 v131, v37, v37
	v_fmac_f32_e32 v130, v34, v34
	v_fmac_f32_e32 v131, v36, v36
	v_add_f32_e32 v130, v130, v131
	v_add_f32_e32 v137, v130, v137
	ds_bpermute_b32 v145, v240, v137
	v_mul_f32_e32 v138, v31, v31
	v_mul_f32_e32 v131, v33, v33
	v_fmac_f32_e32 v138, v30, v30
	v_fmac_f32_e32 v131, v32, v32
	v_add_f32_e32 v138, v138, v131
	v_mul_f32_e32 v130, v27, v27
	v_mul_f32_e32 v131, v29, v29
	v_fmac_f32_e32 v130, v26, v26
	v_fmac_f32_e32 v131, v28, v28
	v_add_f32_e32 v130, v130, v131
	v_add_f32_e32 v138, v130, v138
	v_mul_f32_e32 v130, v23, v23
	v_mul_f32_e32 v131, v25, v25
	v_fmac_f32_e32 v130, v22, v22
	v_fmac_f32_e32 v131, v24, v24
	v_add_f32_e32 v130, v130, v131
	v_add_f32_e32 v138, v130, v138
	v_mul_f32_e32 v130, v19, v19
	v_mul_f32_e32 v131, v21, v21
	v_fmac_f32_e32 v130, v18, v18
	v_fmac_f32_e32 v131, v20, v20
	v_add_f32_e32 v130, v130, v131
	v_add_f32_e32 v138, v130, v138
	ds_bpermute_b32 v146, v240, v138
	v_mul_f32_e32 v139, v15, v15
	v_mul_f32_e32 v131, v17, v17
	v_fmac_f32_e32 v139, v14, v14
	v_fmac_f32_e32 v131, v16, v16
	v_add_f32_e32 v139, v139, v131
	v_mul_f32_e32 v130, v11, v11
	v_mul_f32_e32 v131, v13, v13
	v_fmac_f32_e32 v130, v10, v10
	v_fmac_f32_e32 v131, v12, v12
	v_add_f32_e32 v130, v130, v131
	v_add_f32_e32 v139, v130, v139
	v_mul_f32_e32 v130, v7, v7
	v_mul_f32_e32 v131, v9, v9
	v_fmac_f32_e32 v130, v6, v6
	v_fmac_f32_e32 v131, v8, v8
	v_add_f32_e32 v130, v130, v131
	v_add_f32_e32 v139, v130, v139
	v_mul_f32_e32 v130, v3, v3
	v_mul_f32_e32 v131, v5, v5
	v_fmac_f32_e32 v130, v2, v2
	v_fmac_f32_e32 v131, v4, v4
	v_add_f32_e32 v130, v130, v131
	v_add_f32_e32 v139, v130, v139
	ds_bpermute_b32 v147, v240, v139
	s_waitcnt lgkmcnt(0)
; __device__ __forceinline__ float shx(float v, int o, int lane) { return __builtin_bit_cast(float, __builtin_amdgcn_ds_bpermute((lane ^ o) << 2, __builtin_bit_cast(int, v))); }
; __device__ __forceinline__ void panel_ss_publish(const f32x4 (&v)[2][2][4][2], const Unit& u, int wr, int wc, int fr, int fq, PG8_LAS unsigned char* lds, int wid, int lane, float* slots, unsigned* cnt) {
;     ...
;             s += shx(s, 16, lane); s += shx(s, 32, lane);
;             if (fq == 0) P[(ai * HALF + wr * 64 + m * 16 + fr) * 4 + wc] = s; }
	v_add_f32_e32 v132, v132, v140
	ds_bpermute_b32 v140, v241, v132
	v_add_f32_e32 v133, v133, v141
	ds_bpermute_b32 v141, v241, v133
	v_add_f32_e32 v134, v134, v142
	ds_bpermute_b32 v142, v241, v134
	v_add_f32_e32 v135, v135, v143
	ds_bpermute_b32 v143, v241, v135
	v_add_f32_e32 v136, v136, v144
	ds_bpermute_b32 v144, v241, v136
	v_add_f32_e32 v137, v137, v145
	ds_bpermute_b32 v145, v241, v137
	v_add_f32_e32 v138, v138, v146
	ds_bpermute_b32 v146, v241, v138
	v_add_f32_e32 v139, v139, v147
	ds_bpermute_b32 v147, v241, v139
	s_and_saveexec_b64 s[0:1], s[6:7]
	s_cbranch_execz .Lpub0_skip
	s_waitcnt lgkmcnt(0)
	v_lshl_add_u32 v130, v238, 4, s2
	v_add_f32_e32 v132, v132, v140
	ds_write_b32 v130, v132
	v_add_f32_e32 v133, v133, v141
	ds_write_b32 v130, v133 offset:256
	v_add_f32_e32 v134, v134, v142
	ds_write_b32 v130, v134 offset:512
	v_add_f32_e32 v135, v135, v143
	ds_write_b32 v130, v135 offset:768
	v_add_f32_e32 v136, v136, v144
	ds_write_b32 v130, v136 offset:2048
	v_add_f32_e32 v137, v137, v145
	ds_write_b32 v130, v137 offset:2304
	v_add_f32_e32 v138, v138, v146
	ds_write_b32 v130, v138 offset:2560
	v_add_f32_e32 v139, v139, v147
	ds_write_b32 v130, v139 offset:2816

;     __device__ __forceinline__ void run(f32x4 (&acc)[2][2][4][2], const Unit& u, int wr, int wc, int fr, int fq, PG8_LAS unsigned char* lds, int wid, int lane) const {
;     ...
;         { f32x4 g[2][2];
; #pragma unroll
;           for (int bj = 0; bj < 2; ++bj)
; #pragma unroll
;               for (int n = 0; n < 2; ++n) g[bj][n] = *(const f32x4*)(g_post + col0 + bj * HALF + 4 * n);
; #pragma unroll
;           for (int ai = 0; ai < 2; ++ai)
; #pragma unroll
;               for (int m = 0; m < 4; ++m) { const int r = ai * HALF + wr * 64 + m * 16 + fr; const float rs = coef / sqrtf(S[r] * (1.0f / 1024.0f) + 1e-6f);
; #pragma unroll
;                   for (int bj = 0; bj < 2; ++bj) { f32x4 x0, x1; unpack8(pre[ai][m][bj], x0, x1);
;                       acc[ai][bj][m][0] = x0 + acc[ai][bj][m][0] * g[bj][0] * rs; acc[ai][bj][m][1] = x1 + acc[ai][bj][m][1] * g[bj][1] * rs; } } }
.LBB0_180:
	s_or_b64 exec, exec, s[18:19]
	s_waitcnt lgkmcnt(0)
	s_barrier
	v_lshl_add_u64 v[150:151], v[212:213], 2, s[14:15]
	global_load_dwordx4 v[154:157], v[150:151], off offset:16
	global_load_dwordx4 v[158:161], v[150:151], off
	global_load_dwordx4 v[142:145], v[150:151], off offset:528
	s_nop 0
	global_load_dwordx4 v[150:153], v[150:151], off offset:512
	s_add_u32 s2, s96, 0x15b00000
	s_addc_u32 s3, s97, 0
	s_add_u32 s5, s96, 0x15908000
	s_addc_u32 s34, s97, 0
	s_and_b32 s4, s4, 0xffffff00
	s_add_i32 s4, s4, 0
	v_lshl_add_u32 v0, v238, 2, s4
	v_add_u32_e32 v243, 0x1000, v0
	ds_read2_b32 v[224:225], v243 offset1:16
	s_cmp_eq_u64 s[22:23], 0
	s_cselect_b64 s[18:19], -1, 0
	s_cmp_lg_u64 s[22:23], 0
	s_waitcnt lgkmcnt(0)
	v_fmamk_f32 v0, v224, 0x3a800000, v230
	v_cmp_gt_f32_e32 vcc, s80, v0
	v_mul_f32_e32 v224, 0x4f800000, v0
	s_waitcnt vmcnt(0)
	v_pk_mul_f32 v[124:125], v[124:125], v[156:157]
	v_cndmask_b32_e32 v0, v0, v224, vcc
	v_sqrt_f32_e32 v224, v0
	v_pk_mul_f32 v[128:129], v[128:129], v[160:161]
	v_pk_mul_f32 v[126:127], v[126:127], v[158:159]
	v_pk_mul_f32 v[122:123], v[122:123], v[154:155]
	v_add_u32_e32 v244, -1, v224
	v_fma_f32 v245, -v244, v224, v0
	v_cmp_ge_f32_e64 s[14:15], 0, v245
	v_add_u32_e32 v245, 1, v224
	v_pk_mul_f32 v[120:121], v[120:121], v[152:153]
	v_cndmask_b32_e64 v244, v224, v244, s[14:15]
	v_fma_f32 v224, -v245, v224, v0
	v_cmp_lt_f32_e64 s[14:15], 0, v224
	v_pk_mul_f32 v[118:119], v[118:119], v[150:151]
	v_pk_mul_f32 v[116:117], v[116:117], v[144:145]
	v_cndmask_b32_e64 v224, v244, v245, s[14:15]
	v_mul_f32_e32 v244, 0x37800000, v224
	v_cndmask_b32_e32 v224, v224, v244, vcc
	v_cmp_class_f32_e32 vcc, v0, v231
	v_pk_mul_f32 v[114:115], v[114:115], v[142:143]
	v_pk_mul_f32 v[112:113], v[112:113], v[160:161]
	v_cndmask_b32_e32 v0, v224, v0, vcc
	v_div_scale_f32 v224, s[14:15], v0, v0, s31
	v_rcp_f32_e32 v244, v224
	v_pk_mul_f32 v[104:105], v[104:105], v[152:153]
	v_pk_mul_f32 v[108:109], v[108:109], v[156:157]
	v_pk_mul_f32 v[110:111], v[110:111], v[158:159]
	v_fma_f32 v245, -v224, v244, 1.0
	v_fmac_f32_e32 v244, v245, v244
	v_div_scale_f32 v245, vcc, s31, v0, s31
	v_mul_f32_e32 v246, v245, v244
	v_fma_f32 v247, -v224, v246, v245
	v_fmac_f32_e32 v246, v247, v244
	v_fma_f32 v224, -v224, v246, v245
	v_div_fmas_f32 v224, v224, v244, v246
	v_div_fixup_f32 v0, v224, v0, s31
	v_lshlrev_b32_e32 v244, 16, v206
	v_and_b32_e32 v245, 0xffff0000, v206
	v_lshlrev_b32_e32 v206, 16, v207
	v_and_b32_e32 v207, 0xffff0000, v207
	v_lshlrev_b32_e32 v246, 16, v208
	v_and_b32_e32 v247, 0xffff0000, v208
	v_lshlrev_b32_e32 v208, 16, v209
	v_and_b32_e32 v209, 0xffff0000, v209
	v_pk_fma_f32 v[128:129], v[128:129], v[0:1], v[206:207] op_sel_hi:[1,0,1]
	v_pk_fma_f32 v[124:125], v[124:125], v[0:1], v[208:209] op_sel_hi:[1,0,1]
	v_lshlrev_b32_e32 v206, 16, v202
	v_and_b32_e32 v207, 0xffff0000, v202
	v_lshlrev_b32_e32 v202, 16, v203
	v_and_b32_e32 v203, 0xffff0000, v203
	v_lshlrev_b32_e32 v208, 16, v204
	v_and_b32_e32 v209, 0xffff0000, v204
	v_lshlrev_b32_e32 v204, 16, v205
	v_and_b32_e32 v205, 0xffff0000, v205
	v_pk_fma_f32 v[126:127], v[126:127], v[0:1], v[244:245] op_sel_hi:[1,0,1]
	v_pk_fma_f32 v[122:123], v[122:123], v[0:1], v[246:247] op_sel_hi:[1,0,1]
	v_pk_fma_f32 v[120:121], v[120:121], v[0:1], v[202:203] op_sel_hi:[1,0,1]
	v_pk_fma_f32 v[118:119], v[118:119], v[0:1], v[206:207] op_sel_hi:[1,0,1]
	v_pk_fma_f32 v[116:117], v[116:117], v[0:1], v[204:205] op_sel_hi:[1,0,1]
	v_pk_fma_f32 v[114:115], v[114:115], v[0:1], v[208:209] op_sel_hi:[1,0,1]
	v_fmamk_f32 v0, v225, 0x3a800000, v230
	v_cmp_gt_f32_e32 vcc, s80, v0
	v_mul_f32_e32 v202, 0x4f800000, v0
	v_pk_mul_f32 v[106:107], v[106:107], v[154:155]
	v_cndmask_b32_e32 v0, v0, v202, vcc
	v_sqrt_f32_e32 v202, v0
	v_pk_mul_f32 v[102:103], v[102:103], v[150:151]
	v_pk_mul_f32 v[100:101], v[100:101], v[144:145]
	v_pk_mul_f32 v[98:99], v[98:99], v[142:143]
	v_add_u32_e32 v203, -1, v202
	v_fma_f32 v204, -v203, v202, v0
	v_cmp_ge_f32_e64 s[14:15], 0, v204
	v_add_u32_e32 v204, 1, v202
	v_pk_mul_f32 v[96:97], v[96:97], v[160:161]
	v_cndmask_b32_e64 v203, v202, v203, s[14:15]
	v_fma_f32 v202, -v204, v202, v0
	v_cmp_lt_f32_e64 s[14:15], 0, v202
	v_pk_mul_f32 v[92:93], v[92:93], v[156:157]
	v_pk_mul_f32 v[94:95], v[94:95], v[158:159]
	v_cndmask_b32_e64 v202, v203, v204, s[14:15]
	v_mul_f32_e32 v203, 0x37800000, v202
	v_cndmask_b32_e32 v202, v202, v203, vcc
	v_cmp_class_f32_e32 vcc, v0, v231
	v_pk_mul_f32 v[90:91], v[90:91], v[154:155]
	v_pk_mul_f32 v[88:89], v[88:89], v[152:153]
	v_cndmask_b32_e32 v0, v202, v0, vcc
	v_div_scale_f32 v202, s[14:15], v0, v0, s31
	v_rcp_f32_e32 v203, v202
	v_pk_mul_f32 v[86:87], v[86:87], v[150:151]
	v_pk_mul_f32 v[84:85], v[84:85], v[144:145]
	v_pk_mul_f32 v[82:83], v[82:83], v[142:143]
	v_fma_f32 v204, -v202, v203, 1.0
	v_fmac_f32_e32 v203, v204, v203
	v_div_scale_f32 v204, vcc, s31, v0, s31
	v_mul_f32_e32 v205, v204, v203
	v_fma_f32 v206, -v202, v205, v204
	v_fmac_f32_e32 v205, v206, v203
	v_fma_f32 v202, -v202, v205, v204
	v_div_fmas_f32 v202, v202, v203, v205
	v_div_fixup_f32 v0, v202, v0, s31
	v_lshlrev_b32_e32 v202, 16, v198
	v_and_b32_e32 v203, 0xffff0000, v198
	v_lshlrev_b32_e32 v198, 16, v199
	v_and_b32_e32 v199, 0xffff0000, v199
	v_pk_fma_f32 v[112:113], v[112:113], v[0:1], v[198:199] op_sel_hi:[1,0,1]
	v_lshlrev_b32_e32 v198, 16, v194
	v_and_b32_e32 v199, 0xffff0000, v194
	v_lshlrev_b32_e32 v194, 16, v195
	v_and_b32_e32 v195, 0xffff0000, v195
	v_pk_fma_f32 v[104:105], v[104:105], v[0:1], v[194:195] op_sel_hi:[1,0,1]
	ds_read2_b32 v[194:195], v243 offset0:32 offset1:48
	v_lshlrev_b32_e32 v204, 16, v200
	v_and_b32_e32 v205, 0xffff0000, v200
	v_lshlrev_b32_e32 v200, 16, v201
	v_and_b32_e32 v201, 0xffff0000, v201
	v_pk_fma_f32 v[108:109], v[108:109], v[0:1], v[200:201] op_sel_hi:[1,0,1]
	v_lshlrev_b32_e32 v200, 16, v196
	v_and_b32_e32 v201, 0xffff0000, v196
	v_lshlrev_b32_e32 v196, 16, v197
	v_and_b32_e32 v197, 0xffff0000, v197
	v_pk_fma_f32 v[110:111], v[110:111], v[0:1], v[202:203] op_sel_hi:[1,0,1]
	v_pk_fma_f32 v[106:107], v[106:107], v[0:1], v[204:205] op_sel_hi:[1,0,1]
	v_pk_fma_f32 v[102:103], v[102:103], v[0:1], v[198:199] op_sel_hi:[1,0,1]
	v_pk_fma_f32 v[100:101], v[100:101], v[0:1], v[196:197] op_sel_hi:[1,0,1]
	v_pk_fma_f32 v[98:99], v[98:99], v[0:1], v[200:201] op_sel_hi:[1,0,1]
	s_waitcnt lgkmcnt(0)
;     __device__ __forceinline__ void run(f32x4 (&acc)[2][2][4][2], const Unit& u, int wr, int wc, int fr, int fq, PG8_LAS unsigned char* lds, int wid, int lane) const {
;     ...
;           for (int ai = 0; ai < 2; ++ai)
; #pragma unroll
;               for (int m = 0; m < 4; ++m) { const int r = ai * HALF + wr * 64 + m * 16 + fr; const float rs = coef / sqrtf(S[r] * (1.0f / 1024.0f) + 1e-6f);
; #pragma unroll
;                   for (int bj = 0; bj < 2; ++bj) { f32x4 x0, x1; unpack8(pre[ai][m][bj], x0, x1);
;                       acc[ai][bj][m][0] = x0 + acc[ai][bj][m][0] * g[bj][0] * rs; acc[ai][bj][m][1] = x1 + acc[ai][bj][m][1] * g[bj][1] * rs; } } }
	v_fmamk_f32 v0, v194, 0x3a800000, v230
	v_cmp_gt_f32_e32 vcc, s80, v0
	v_mul_f32_e32 v194, 0x4f800000, v0
	v_pk_mul_f32 v[80:81], v[80:81], v[160:161]
	v_cndmask_b32_e32 v0, v0, v194, vcc
	v_sqrt_f32_e32 v194, v0
	v_pk_mul_f32 v[72:73], v[72:73], v[152:153]
	v_pk_mul_f32 v[76:77], v[76:77], v[156:157]
	v_pk_mul_f32 v[78:79], v[78:79], v[158:159]
	v_add_u32_e32 v196, -1, v194
	v_fma_f32 v197, -v196, v194, v0
	v_cmp_ge_f32_e64 s[14:15], 0, v197
	v_add_u32_e32 v197, 1, v194
	v_pk_mul_f32 v[74:75], v[74:75], v[154:155]
	v_cndmask_b32_e64 v196, v194, v196, s[14:15]
	v_fma_f32 v194, -v197, v194, v0
	v_cmp_lt_f32_e64 s[14:15], 0, v194
	v_pk_mul_f32 v[70:71], v[70:71], v[150:151]
	v_pk_mul_f32 v[68:69], v[68:69], v[144:145]
	v_cndmask_b32_e64 v194, v196, v197, s[14:15]
	v_mul_f32_e32 v196, 0x37800000, v194
	v_cndmask_b32_e32 v194, v194, v196, vcc
	v_cmp_class_f32_e32 vcc, v0, v231
	v_pk_mul_f32 v[66:67], v[66:67], v[142:143]
	v_pk_mul_f32 v[64:65], v[64:65], v[160:161]
	v_cndmask_b32_e32 v0, v194, v0, vcc
	v_div_scale_f32 v194, s[14:15], v0, v0, s31
	v_rcp_f32_e32 v196, v194
	v_pk_mul_f32 v[60:61], v[60:61], v[156:157]
	v_pk_mul_f32 v[62:63], v[62:63], v[158:159]
	v_pk_mul_f32 v[58:59], v[58:59], v[154:155]
	v_fma_f32 v197, -v194, v196, 1.0
	v_fmac_f32_e32 v196, v197, v196
	v_div_scale_f32 v197, vcc, s31, v0, s31
	v_mul_f32_e32 v198, v197, v196
	v_fma_f32 v199, -v194, v198, v197
	v_fmac_f32_e32 v198, v199, v196
	v_fma_f32 v194, -v194, v198, v197
	v_div_fmas_f32 v194, v194, v196, v198
	v_div_fixup_f32 v0, v194, v0, s31
	v_lshlrev_b32_e32 v196, 16, v190
	v_and_b32_e32 v197, 0xffff0000, v190
	v_lshlrev_b32_e32 v190, 16, v191
	v_and_b32_e32 v191, 0xffff0000, v191
	v_lshlrev_b32_e32 v198, 16, v192
	v_and_b32_e32 v199, 0xffff0000, v192
	v_lshlrev_b32_e32 v192, 16, v193
	v_and_b32_e32 v193, 0xffff0000, v193
	v_pk_fma_f32 v[96:97], v[96:97], v[0:1], v[190:191] op_sel_hi:[1,0,1]
	v_pk_fma_f32 v[92:93], v[92:93], v[0:1], v[192:193] op_sel_hi:[1,0,1]
	v_lshlrev_b32_e32 v190, 16, v186
	v_and_b32_e32 v191, 0xffff0000, v186
	v_lshlrev_b32_e32 v186, 16, v187
	v_and_b32_e32 v187, 0xffff0000, v187
	v_lshlrev_b32_e32 v192, 16, v188
	v_and_b32_e32 v193, 0xffff0000, v188
	v_lshlrev_b32_e32 v188, 16, v189
	v_and_b32_e32 v189, 0xffff0000, v189
	v_pk_fma_f32 v[94:95], v[94:95], v[0:1], v[196:197] op_sel_hi:[1,0,1]
	v_pk_fma_f32 v[90:91], v[90:91], v[0:1], v[198:199] op_sel_hi:[1,0,1]
	v_pk_fma_f32 v[88:89], v[88:89], v[0:1], v[186:187] op_sel_hi:[1,0,1]
	v_pk_fma_f32 v[86:87], v[86:87], v[0:1], v[190:191] op_sel_hi:[1,0,1]
	v_pk_fma_f32 v[84:85], v[84:85], v[0:1], v[188:189] op_sel_hi:[1,0,1]
	v_pk_fma_f32 v[82:83], v[82:83], v[0:1], v[192:193] op_sel_hi:[1,0,1]
	v_fmamk_f32 v0, v195, 0x3a800000, v230
	v_cmp_gt_f32_e32 vcc, s80, v0
	v_mul_f32_e32 v186, 0x4f800000, v0
	v_pk_mul_f32 v[56:57], v[56:57], v[152:153]
	v_cndmask_b32_e32 v0, v0, v186, vcc
	v_sqrt_f32_e32 v186, v0
	v_pk_mul_f32 v[54:55], v[54:55], v[150:151]
	v_pk_mul_f32 v[52:53], v[52:53], v[144:145]
	v_pk_mul_f32 v[50:51], v[50:51], v[142:143]
	v_add_u32_e32 v187, -1, v186
	v_fma_f32 v188, -v187, v186, v0
	v_cmp_ge_f32_e64 s[14:15], 0, v188
	v_add_u32_e32 v188, 1, v186
	v_pk_mul_f32 v[48:49], v[48:49], v[160:161]
	v_cndmask_b32_e64 v187, v186, v187, s[14:15]
	v_fma_f32 v186, -v188, v186, v0
	v_cmp_lt_f32_e64 s[14:15], 0, v186
	v_pk_mul_f32 v[40:41], v[40:41], v[152:153]
	v_pk_mul_f32 v[44:45], v[44:45], v[156:157]
	v_cndmask_b32_e64 v186, v187, v188, s[14:15]
	v_mul_f32_e32 v187, 0x37800000, v186
	v_cndmask_b32_e32 v186, v186, v187, vcc
	v_cmp_class_f32_e32 vcc, v0, v231
	v_pk_mul_f32 v[46:47], v[46:47], v[158:159]
	v_pk_mul_f32 v[42:43], v[42:43], v[154:155]
	v_cndmask_b32_e32 v0, v186, v0, vcc
	v_div_scale_f32 v186, s[14:15], v0, v0, s31
	v_rcp_f32_e32 v187, v186
	v_pk_mul_f32 v[38:39], v[38:39], v[150:151]
	v_pk_mul_f32 v[36:37], v[36:37], v[144:145]
	v_pk_mul_f32 v[34:35], v[34:35], v[142:143]
	v_fma_f32 v188, -v186, v187, 1.0
	v_fmac_f32_e32 v187, v188, v187
	v_div_scale_f32 v188, vcc, s31, v0, s31
	v_mul_f32_e32 v189, v188, v187
	v_fma_f32 v190, -v186, v189, v188
	v_fmac_f32_e32 v189, v190, v187
	v_fma_f32 v186, -v186, v189, v188
	v_div_fmas_f32 v186, v186, v187, v189
	v_div_fixup_f32 v0, v186, v0, s31
	v_lshlrev_b32_e32 v186, 16, v182
	v_and_b32_e32 v187, 0xffff0000, v182
	v_lshlrev_b32_e32 v182, 16, v183
	v_and_b32_e32 v183, 0xffff0000, v183
	v_pk_fma_f32 v[80:81], v[80:81], v[0:1], v[182:183] op_sel_hi:[1,0,1]
	v_lshlrev_b32_e32 v182, 16, v178
	v_and_b32_e32 v183, 0xffff0000, v178
	v_lshlrev_b32_e32 v178, 16, v179
	v_and_b32_e32 v179, 0xffff0000, v179
	v_pk_fma_f32 v[72:73], v[72:73], v[0:1], v[178:179] op_sel_hi:[1,0,1]
	ds_read2_b32 v[178:179], v243 offset0:128 offset1:144
	v_lshlrev_b32_e32 v188, 16, v184
	v_and_b32_e32 v189, 0xffff0000, v184
	v_lshlrev_b32_e32 v184, 16, v185
	v_and_b32_e32 v185, 0xffff0000, v185
	v_pk_fma_f32 v[76:77], v[76:77], v[0:1], v[184:185] op_sel_hi:[1,0,1]
	v_lshlrev_b32_e32 v184, 16, v180
	v_and_b32_e32 v185, 0xffff0000, v180
	v_lshlrev_b32_e32 v180, 16, v181
	v_and_b32_e32 v181, 0xffff0000, v181
	v_pk_fma_f32 v[78:79], v[78:79], v[0:1], v[186:187] op_sel_hi:[1,0,1]
	v_pk_fma_f32 v[74:75], v[74:75], v[0:1], v[188:189] op_sel_hi:[1,0,1]
	v_pk_fma_f32 v[70:71], v[70:71], v[0:1], v[182:183] op_sel_hi:[1,0,1]
	v_pk_fma_f32 v[68:69], v[68:69], v[0:1], v[180:181] op_sel_hi:[1,0,1]
	v_pk_fma_f32 v[66:67], v[66:67], v[0:1], v[184:185] op_sel_hi:[1,0,1]
	s_waitcnt lgkmcnt(0)
;     __device__ __forceinline__ void run(f32x4 (&acc)[2][2][4][2], const Unit& u, int wr, int wc, int fr, int fq, PG8_LAS unsigned char* lds, int wid, int lane) const {
;     ...
;           for (int ai = 0; ai < 2; ++ai)
; #pragma unroll
;               for (int m = 0; m < 4; ++m) { const int r = ai * HALF + wr * 64 + m * 16 + fr; const float rs = coef / sqrtf(S[r] * (1.0f / 1024.0f) + 1e-6f);
; #pragma unroll
;                   for (int bj = 0; bj < 2; ++bj) { f32x4 x0, x1; unpack8(pre[ai][m][bj], x0, x1);
;                       acc[ai][bj][m][0] = x0 + acc[ai][bj][m][0] * g[bj][0] * rs; acc[ai][bj][m][1] = x1 + acc[ai][bj][m][1] * g[bj][1] * rs; } } }
	v_fmamk_f32 v0, v178, 0x3a800000, v230
	v_cmp_gt_f32_e32 vcc, s80, v0
	v_mul_f32_e32 v178, 0x4f800000, v0
	v_pk_mul_f32 v[32:33], v[32:33], v[160:161]
	v_cndmask_b32_e32 v0, v0, v178, vcc
	v_sqrt_f32_e32 v178, v0
	v_pk_mul_f32 v[28:29], v[28:29], v[156:157]
	v_pk_mul_f32 v[30:31], v[30:31], v[158:159]
	v_pk_mul_f32 v[26:27], v[26:27], v[154:155]
	v_add_u32_e32 v180, -1, v178
	v_fma_f32 v181, -v180, v178, v0
	v_cmp_ge_f32_e64 s[14:15], 0, v181
	v_add_u32_e32 v181, 1, v178
	v_pk_mul_f32 v[24:25], v[24:25], v[152:153]
	v_cndmask_b32_e64 v180, v178, v180, s[14:15]
	v_fma_f32 v178, -v181, v178, v0
	v_cmp_lt_f32_e64 s[14:15], 0, v178
	v_pk_mul_f32 v[22:23], v[22:23], v[150:151]
	v_pk_mul_f32 v[20:21], v[20:21], v[144:145]
	v_cndmask_b32_e64 v178, v180, v181, s[14:15]
	v_mul_f32_e32 v180, 0x37800000, v178
	v_cndmask_b32_e32 v178, v178, v180, vcc
	v_cmp_class_f32_e32 vcc, v0, v231
	v_pk_mul_f32 v[18:19], v[18:19], v[142:143]
	v_pk_mul_f32 v[16:17], v[16:17], v[160:161]
	v_cndmask_b32_e32 v0, v178, v0, vcc
	v_div_scale_f32 v178, s[14:15], v0, v0, s31
	v_rcp_f32_e32 v180, v178
	v_pk_mul_f32 v[12:13], v[12:13], v[156:157]
	v_pk_mul_f32 v[14:15], v[14:15], v[158:159]
	v_pk_mul_f32 v[10:11], v[10:11], v[154:155]
	v_fma_f32 v181, -v178, v180, 1.0
	v_fmac_f32_e32 v180, v181, v180
	v_div_scale_f32 v181, vcc, s31, v0, s31
	v_mul_f32_e32 v182, v181, v180
	v_fma_f32 v183, -v178, v182, v181
	v_fmac_f32_e32 v182, v183, v180
	v_fma_f32 v178, -v178, v182, v181
	v_div_fmas_f32 v178, v178, v180, v182
	v_div_fixup_f32 v0, v178, v0, s31
	v_lshlrev_b32_e32 v180, 16, v174
	v_and_b32_e32 v181, 0xffff0000, v174
	v_lshlrev_b32_e32 v174, 16, v175
	v_and_b32_e32 v175, 0xffff0000, v175
	v_lshlrev_b32_e32 v182, 16, v176
	v_and_b32_e32 v183, 0xffff0000, v176
	v_lshlrev_b32_e32 v176, 16, v177
	v_and_b32_e32 v177, 0xffff0000, v177
	v_pk_fma_f32 v[64:65], v[64:65], v[0:1], v[174:175] op_sel_hi:[1,0,1]
	v_pk_fma_f32 v[60:61], v[60:61], v[0:1], v[176:177] op_sel_hi:[1,0,1]
	v_lshlrev_b32_e32 v174, 16, v170
	v_and_b32_e32 v175, 0xffff0000, v170
	v_lshlrev_b32_e32 v170, 16, v171
	v_and_b32_e32 v171, 0xffff0000, v171
	v_lshlrev_b32_e32 v176, 16, v172
	v_and_b32_e32 v177, 0xffff0000, v172
	v_lshlrev_b32_e32 v172, 16, v173
	v_and_b32_e32 v173, 0xffff0000, v173
	v_pk_fma_f32 v[62:63], v[62:63], v[0:1], v[180:181] op_sel_hi:[1,0,1]
	v_pk_fma_f32 v[58:59], v[58:59], v[0:1], v[182:183] op_sel_hi:[1,0,1]
	v_pk_fma_f32 v[56:57], v[56:57], v[0:1], v[170:171] op_sel_hi:[1,0,1]
	v_pk_fma_f32 v[54:55], v[54:55], v[0:1], v[174:175] op_sel_hi:[1,0,1]
	v_pk_fma_f32 v[52:53], v[52:53], v[0:1], v[172:173] op_sel_hi:[1,0,1]
	v_pk_fma_f32 v[50:51], v[50:51], v[0:1], v[176:177] op_sel_hi:[1,0,1]
	v_fmamk_f32 v0, v179, 0x3a800000, v230
	v_cmp_gt_f32_e32 vcc, s80, v0
	v_mul_f32_e32 v170, 0x4f800000, v0
	v_pk_mul_f32 v[8:9], v[8:9], v[152:153]
	v_cndmask_b32_e32 v0, v0, v170, vcc
	v_sqrt_f32_e32 v170, v0
	v_pk_mul_f32 v[6:7], v[6:7], v[150:151]
	v_pk_mul_f32 v[4:5], v[4:5], v[144:145]
	v_pk_mul_f32 v[2:3], v[2:3], v[142:143]
	v_add_u32_e32 v171, -1, v170
	v_fma_f32 v172, -v171, v170, v0
	v_cmp_ge_f32_e64 s[14:15], 0, v172
	v_add_u32_e32 v172, 1, v170
	s_nop 0
	v_cndmask_b32_e64 v171, v170, v171, s[14:15]
	v_fma_f32 v170, -v172, v170, v0
	v_cmp_lt_f32_e64 s[14:15], 0, v170
	s_nop 1
	v_cndmask_b32_e64 v170, v171, v172, s[14:15]
	v_mul_f32_e32 v171, 0x37800000, v170
	v_cndmask_b32_e32 v170, v170, v171, vcc
	v_cmp_class_f32_e32 vcc, v0, v231
	s_nop 1
	v_cndmask_b32_e32 v0, v170, v0, vcc
	v_div_scale_f32 v170, s[14:15], v0, v0, s31
	v_rcp_f32_e32 v171, v170
	s_nop 0
	v_fma_f32 v172, -v170, v171, 1.0
	v_fmac_f32_e32 v171, v172, v171
	v_div_scale_f32 v172, vcc, s31, v0, s31
	v_mul_f32_e32 v173, v172, v171
	v_fma_f32 v174, -v170, v173, v172
	v_fmac_f32_e32 v173, v174, v171
	v_fma_f32 v170, -v170, v173, v172
	v_div_fmas_f32 v170, v170, v171, v173
	v_div_fixup_f32 v0, v170, v0, s31
	v_lshlrev_b32_e32 v170, 16, v166
	v_and_b32_e32 v171, 0xffff0000, v166
	v_lshlrev_b32_e32 v166, 16, v167
	v_and_b32_e32 v167, 0xffff0000, v167
	v_pk_fma_f32 v[48:49], v[48:49], v[0:1], v[166:167] op_sel_hi:[1,0,1]
	v_lshlrev_b32_e32 v166, 16, v162
	v_and_b32_e32 v167, 0xffff0000, v162
	v_lshlrev_b32_e32 v162, 16, v163
	v_and_b32_e32 v163, 0xffff0000, v163
	v_pk_fma_f32 v[40:41], v[40:41], v[0:1], v[162:163] op_sel_hi:[1,0,1]
	ds_read2_b32 v[162:163], v243 offset0:160 offset1:176
	v_lshlrev_b32_e32 v172, 16, v168
	v_and_b32_e32 v173, 0xffff0000, v168
	v_lshlrev_b32_e32 v168, 16, v169
	v_and_b32_e32 v169, 0xffff0000, v169
	v_pk_fma_f32 v[44:45], v[44:45], v[0:1], v[168:169] op_sel_hi:[1,0,1]
	v_lshlrev_b32_e32 v168, 16, v164
	v_and_b32_e32 v169, 0xffff0000, v164
	v_lshlrev_b32_e32 v164, 16, v165
	v_and_b32_e32 v165, 0xffff0000, v165
	v_pk_fma_f32 v[46:47], v[46:47], v[0:1], v[170:171] op_sel_hi:[1,0,1]
	v_pk_fma_f32 v[42:43], v[42:43], v[0:1], v[172:173] op_sel_hi:[1,0,1]
	v_pk_fma_f32 v[38:39], v[38:39], v[0:1], v[166:167] op_sel_hi:[1,0,1]
	v_pk_fma_f32 v[36:37], v[36:37], v[0:1], v[164:165] op_sel_hi:[1,0,1]
	v_pk_fma_f32 v[34:35], v[34:35], v[0:1], v[168:169] op_sel_hi:[1,0,1]
	s_waitcnt lgkmcnt(0)
;     __device__ __forceinline__ void run(f32x4 (&acc)[2][2][4][2], const Unit& u, int wr, int wc, int fr, int fq, PG8_LAS unsigned char* lds, int wid, int lane) const {
;     ...
;           for (int ai = 0; ai < 2; ++ai)
; #pragma unroll
;               for (int m = 0; m < 4; ++m) { const int r = ai * HALF + wr * 64 + m * 16 + fr; const float rs = coef / sqrtf(S[r] * (1.0f / 1024.0f) + 1e-6f);
; #pragma unroll
;                   for (int bj = 0; bj < 2; ++bj) { f32x4 x0, x1; unpack8(pre[ai][m][bj], x0, x1);
;                       acc[ai][bj][m][0] = x0 + acc[ai][bj][m][0] * g[bj][0] * rs; acc[ai][bj][m][1] = x1 + acc[ai][bj][m][1] * g[bj][1] * rs; } } }
;         if (!fout) panel_ss_publish(acc, u, wr, wc, fr, fq, lds, wid, lane, slots2, cnt2);
	v_fmamk_f32 v0, v162, 0x3a800000, v230
	v_cmp_gt_f32_e32 vcc, s80, v0
	v_mul_f32_e32 v162, 0x4f800000, v0
	s_nop 0
	v_cndmask_b32_e32 v0, v0, v162, vcc
	v_sqrt_f32_e32 v162, v0
	s_nop 0
	v_add_u32_e32 v164, -1, v162
	v_fma_f32 v165, -v164, v162, v0
	v_cmp_ge_f32_e64 s[14:15], 0, v165
	v_add_u32_e32 v165, 1, v162
	s_nop 0
	v_cndmask_b32_e64 v164, v162, v164, s[14:15]
	v_fma_f32 v162, -v165, v162, v0
	v_cmp_lt_f32_e64 s[14:15], 0, v162
	s_nop 1
	v_cndmask_b32_e64 v162, v164, v165, s[14:15]
	v_mul_f32_e32 v164, 0x37800000, v162
	v_cndmask_b32_e32 v162, v162, v164, vcc
	v_cmp_class_f32_e32 vcc, v0, v231
	s_nop 1
	v_cndmask_b32_e32 v0, v162, v0, vcc
	v_div_scale_f32 v162, s[14:15], v0, v0, s31
	v_rcp_f32_e32 v164, v162
	s_nop 0
	v_fma_f32 v165, -v162, v164, 1.0
	v_fmac_f32_e32 v164, v165, v164
	v_div_scale_f32 v165, vcc, s31, v0, s31
	v_mul_f32_e32 v166, v165, v164
	v_fma_f32 v167, -v162, v166, v165
	v_fmac_f32_e32 v166, v167, v164
	v_fma_f32 v162, -v162, v166, v165
	v_div_fmas_f32 v162, v162, v164, v166
	v_div_fixup_f32 v0, v162, v0, s31
	v_lshlrev_b32_e32 v164, 16, v146
	v_and_b32_e32 v165, 0xffff0000, v146
	v_lshlrev_b32_e32 v146, 16, v147
	v_and_b32_e32 v147, 0xffff0000, v147
	v_lshlrev_b32_e32 v166, 16, v148
	v_and_b32_e32 v167, 0xffff0000, v148
	v_lshlrev_b32_e32 v148, 16, v149
	v_and_b32_e32 v149, 0xffff0000, v149
	v_pk_fma_f32 v[32:33], v[32:33], v[0:1], v[146:147] op_sel_hi:[1,0,1]
	v_pk_fma_f32 v[28:29], v[28:29], v[0:1], v[148:149] op_sel_hi:[1,0,1]
	v_lshlrev_b32_e32 v146, 16, v138
	v_and_b32_e32 v147, 0xffff0000, v138
	v_lshlrev_b32_e32 v138, 16, v139
	v_and_b32_e32 v139, 0xffff0000, v139
	v_lshlrev_b32_e32 v148, 16, v140
	v_and_b32_e32 v149, 0xffff0000, v140
	v_lshlrev_b32_e32 v140, 16, v141
	v_and_b32_e32 v141, 0xffff0000, v141
	v_pk_fma_f32 v[30:31], v[30:31], v[0:1], v[164:165] op_sel_hi:[1,0,1]
	v_pk_fma_f32 v[26:27], v[26:27], v[0:1], v[166:167] op_sel_hi:[1,0,1]
	v_pk_fma_f32 v[24:25], v[24:25], v[0:1], v[138:139] op_sel_hi:[1,0,1]
	v_pk_fma_f32 v[22:23], v[22:23], v[0:1], v[146:147] op_sel_hi:[1,0,1]
	v_pk_fma_f32 v[20:21], v[20:21], v[0:1], v[140:141] op_sel_hi:[1,0,1]
	v_pk_fma_f32 v[18:19], v[18:19], v[0:1], v[148:149] op_sel_hi:[1,0,1]
	v_fmamk_f32 v0, v163, 0x3a800000, v230
	v_cmp_gt_f32_e32 vcc, s80, v0
	v_mul_f32_e32 v138, 0x4f800000, v0
	s_nop 0
	v_cndmask_b32_e32 v0, v0, v138, vcc
	v_sqrt_f32_e32 v138, v0
	s_nop 0
	v_add_u32_e32 v139, -1, v138
	v_fma_f32 v140, -v139, v138, v0
	v_cmp_ge_f32_e64 s[14:15], 0, v140
	v_add_u32_e32 v140, 1, v138
	s_nop 0
	v_cndmask_b32_e64 v139, v138, v139, s[14:15]
	v_fma_f32 v138, -v140, v138, v0
	v_cmp_lt_f32_e64 s[14:15], 0, v138
	s_nop 1
	v_cndmask_b32_e64 v138, v139, v140, s[14:15]
	v_mul_f32_e32 v139, 0x37800000, v138
	v_cndmask_b32_e32 v138, v138, v139, vcc
	v_cmp_class_f32_e32 vcc, v0, v231
	s_nop 1
	v_cndmask_b32_e32 v0, v138, v0, vcc
	v_div_scale_f32 v138, s[14:15], v0, v0, s31
	v_rcp_f32_e32 v139, v138
	s_cselect_b64 s[14:15], -1, 0
	v_fma_f32 v140, -v138, v139, 1.0
	v_fmac_f32_e32 v139, v140, v139
	v_div_scale_f32 v140, vcc, s31, v0, s31
	v_mul_f32_e32 v141, v140, v139
	v_fma_f32 v146, -v138, v141, v140
	v_fmac_f32_e32 v141, v146, v139
	v_fma_f32 v138, -v138, v141, v140
	v_div_fmas_f32 v138, v138, v139, v141
	v_div_fixup_f32 v0, v138, v0, s31
	v_lshlrev_b32_e32 v138, 16, v134
	v_and_b32_e32 v139, 0xffff0000, v134
	v_lshlrev_b32_e32 v134, 16, v135
	v_and_b32_e32 v135, 0xffff0000, v135
	v_lshlrev_b32_e32 v140, 16, v136
	v_and_b32_e32 v141, 0xffff0000, v136
	v_lshlrev_b32_e32 v136, 16, v137
	v_and_b32_e32 v137, 0xffff0000, v137
	v_pk_fma_f32 v[16:17], v[16:17], v[0:1], v[134:135] op_sel_hi:[1,0,1]
	v_pk_fma_f32 v[12:13], v[12:13], v[0:1], v[136:137] op_sel_hi:[1,0,1]
	v_lshlrev_b32_e32 v134, 16, v130
	v_and_b32_e32 v135, 0xffff0000, v130
	v_lshlrev_b32_e32 v130, 16, v131
	v_and_b32_e32 v131, 0xffff0000, v131
	v_lshlrev_b32_e32 v136, 16, v132
	v_and_b32_e32 v137, 0xffff0000, v132
	v_lshlrev_b32_e32 v132, 16, v133
	v_and_b32_e32 v133, 0xffff0000, v133
	v_pk_fma_f32 v[14:15], v[14:15], v[0:1], v[138:139] op_sel_hi:[1,0,1]
	v_pk_fma_f32 v[10:11], v[10:11], v[0:1], v[140:141] op_sel_hi:[1,0,1]
	v_pk_fma_f32 v[8:9], v[8:9], v[0:1], v[130:131] op_sel_hi:[1,0,1]
	v_pk_fma_f32 v[6:7], v[6:7], v[0:1], v[134:135] op_sel_hi:[1,0,1]
	v_pk_fma_f32 v[4:5], v[4:5], v[0:1], v[132:133] op_sel_hi:[1,0,1]
	v_pk_fma_f32 v[2:3], v[2:3], v[0:1], v[136:137] op_sel_hi:[1,0,1]
	s_and_b64 vcc, exec, s[14:15]
	s_cbranch_vccnz .LBB0_203
; __device__ __forceinline__ float shx(float v, int o, int lane) { return __builtin_bit_cast(float, __builtin_amdgcn_ds_bpermute((lane ^ o) << 2, __builtin_bit_cast(int, v))); }
; #define PG8_LAS __attribute__((address_space(3)))
; __device__ __forceinline__ void panel_ss_publish(const f32x4 (&v)[2][2][4][2], const Unit& u, int wr, int wc, int fr, int fq, PG8_LAS unsigned char* lds, int wid, int lane, float* slots, unsigned* cnt) {
;     PG8_LAS float* P = (PG8_LAS float*)lds;
; #pragma unroll
;     for (int ai = 0; ai < 2; ++ai)
; #pragma unroll
;         for (int m = 0; m < 4; ++m) { float s = 0.f;
; #pragma unroll
;             for (int bj = 0; bj < 2; ++bj)
; #pragma unroll
;                 for (int n = 0; n < 2; ++n) { const f32x4 x = v[ai][bj][m][n]; s += (x[0] * x[0] + x[1] * x[1]) + (x[2] * x[2] + x[3] * x[3]); }
;             s += shx(s, 16, lane); s += shx(s, 32, lane);
;             if (fq == 0) P[(ai * HALF + wr * 64 + m * 16 + fr) * 4 + wc] = s; }
;     __device__ __forceinline__ void run(f32x4 (&acc)[2][2][4][2], const Unit& u, int wr, int wc, int fr, int fq, PG8_LAS unsigned char* lds, int wid, int lane) const {
;     ...
;         if (!fout) panel_ss_publish(acc, u, wr, wc, fr, fq, lds, wid, lane, slots2, cnt2);
	s_lshl_b32 s4, s57, 10
	s_add_i32 s4, s36, s4
	v_mul_f32_e32 v132, v127, v127
	v_mul_f32_e32 v131, v129, v129
	v_fmac_f32_e32 v132, v126, v126
	v_fmac_f32_e32 v131, v128, v128
	v_add_f32_e32 v132, v132, v131
	v_mul_f32_e32 v130, v123, v123
	v_mul_f32_e32 v131, v125, v125
	v_fmac_f32_e32 v130, v122, v122
	v_fmac_f32_e32 v131, v124, v124
	v_add_f32_e32 v130, v130, v131
	v_add_f32_e32 v132, v130, v132
	v_mul_f32_e32 v130, v119, v119
	v_mul_f32_e32 v131, v121, v121
	v_fmac_f32_e32 v130, v118, v118
	v_fmac_f32_e32 v131, v120, v120
	v_add_f32_e32 v130, v130, v131
	v_add_f32_e32 v132, v130, v132
	v_mul_f32_e32 v130, v115, v115
	v_mul_f32_e32 v131, v117, v117
	v_fmac_f32_e32 v130, v114, v114
	v_fmac_f32_e32 v131, v116, v116
	v_add_f32_e32 v130, v130, v131
	v_add_f32_e32 v132, v130, v132
	ds_bpermute_b32 v140, v240, v132
	v_mul_f32_e32 v133, v111, v111
	v_mul_f32_e32 v131, v113, v113
	v_fmac_f32_e32 v133, v110, v110
	v_fmac_f32_e32 v131, v112, v112
	v_add_f32_e32 v133, v133, v131
	v_mul_f32_e32 v130, v107, v107
	v_mul_f32_e32 v131, v109, v109
	v_fmac_f32_e32 v130, v106, v106
	v_fmac_f32_e32 v131, v108, v108
	v_add_f32_e32 v130, v130, v131
	v_add_f32_e32 v133, v130, v133
	v_mul_f32_e32 v130, v103, v103
	v_mul_f32_e32 v131, v105, v105
	v_fmac_f32_e32 v130, v102, v102
	v_fmac_f32_e32 v131, v104, v104
	v_add_f32_e32 v130, v130, v131
	v_add_f32_e32 v133, v130, v133
	v_mul_f32_e32 v130, v99, v99
	v_mul_f32_e32 v131, v101, v101
	v_fmac_f32_e32 v130, v98, v98
	v_fmac_f32_e32 v131, v100, v100
	v_add_f32_e32 v130, v130, v131
	v_add_f32_e32 v133, v130, v133
	ds_bpermute_b32 v141, v240, v133
	v_mul_f32_e32 v134, v95, v95
	v_mul_f32_e32 v131, v97, v97
	v_fmac_f32_e32 v134, v94, v94
	v_fmac_f32_e32 v131, v96, v96
	v_add_f32_e32 v134, v134, v131
	v_mul_f32_e32 v130, v91, v91
	v_mul_f32_e32 v131, v93, v93
	v_fmac_f32_e32 v130, v90, v90
	v_fmac_f32_e32 v131, v92, v92
	v_add_f32_e32 v130, v130, v131
	v_add_f32_e32 v134, v130, v134
	v_mul_f32_e32 v130, v87, v87
	v_mul_f32_e32 v131, v89, v89
	v_fmac_f32_e32 v130, v86, v86
	v_fmac_f32_e32 v131, v88, v88
	v_add_f32_e32 v130, v130, v131
	v_add_f32_e32 v134, v130, v134
	v_mul_f32_e32 v130, v83, v83
	v_mul_f32_e32 v131, v85, v85
	v_fmac_f32_e32 v130, v82, v82
	v_fmac_f32_e32 v131, v84, v84
	v_add_f32_e32 v130, v130, v131
	v_add_f32_e32 v134, v130, v134
	ds_bpermute_b32 v142, v240, v134
	v_mul_f32_e32 v135, v79, v79
	v_mul_f32_e32 v131, v81, v81
	v_fmac_f32_e32 v135, v78, v78
	v_fmac_f32_e32 v131, v80, v80
	v_add_f32_e32 v135, v135, v131
	v_mul_f32_e32 v130, v75, v75
	v_mul_f32_e32 v131, v77, v77
	v_fmac_f32_e32 v130, v74, v74
	v_fmac_f32_e32 v131, v76, v76
	v_add_f32_e32 v130, v130, v131
	v_add_f32_e32 v135, v130, v135
	v_mul_f32_e32 v130, v71, v71
	v_mul_f32_e32 v131, v73, v73
	v_fmac_f32_e32 v130, v70, v70
	v_fmac_f32_e32 v131, v72, v72
	v_add_f32_e32 v130, v130, v131
	v_add_f32_e32 v135, v130, v135
	v_mul_f32_e32 v130, v67, v67
	v_mul_f32_e32 v131, v69, v69
	v_fmac_f32_e32 v130, v66, v66
	v_fmac_f32_e32 v131, v68, v68
	v_add_f32_e32 v130, v130, v131
	v_add_f32_e32 v135, v130, v135
	ds_bpermute_b32 v143, v240, v135
	v_mul_f32_e32 v136, v63, v63
	v_mul_f32_e32 v131, v65, v65
	v_fmac_f32_e32 v136, v62, v62
	v_fmac_f32_e32 v131, v64, v64
	v_add_f32_e32 v136, v136, v131
	v_mul_f32_e32 v130, v59, v59
	v_mul_f32_e32 v131, v61, v61
	v_fmac_f32_e32 v130, v58, v58
	v_fmac_f32_e32 v131, v60, v60
	v_add_f32_e32 v130, v130, v131
	v_add_f32_e32 v136, v130, v136
	v_mul_f32_e32 v130, v55, v55
	v_mul_f32_e32 v131, v57, v57
	v_fmac_f32_e32 v130, v54, v54
	v_fmac_f32_e32 v131, v56, v56
	v_add_f32_e32 v130, v130, v131
	v_add_f32_e32 v136, v130, v136
	v_mul_f32_e32 v130, v51, v51
	v_mul_f32_e32 v131, v53, v53
	v_fmac_f32_e32 v130, v50, v50
	v_fmac_f32_e32 v131, v52, v52
	v_add_f32_e32 v130, v130, v131
	v_add_f32_e32 v136, v130, v136
	ds_bpermute_b32 v144, v240, v136
	v_mul_f32_e32 v137, v47, v47
	v_mul_f32_e32 v131, v49, v49
	v_fmac_f32_e32 v137, v46, v46
	v_fmac_f32_e32 v131, v48, v48
	v_add_f32_e32 v137, v137, v131
	v_mul_f32_e32 v130, v43, v43
	v_mul_f32_e32 v131, v45, v45
	v_fmac_f32_e32 v130, v42, v42
	v_fmac_f32_e32 v131, v44, v44
	v_add_f32_e32 v130, v130, v131
	v_add_f32_e32 v137, v130, v137
	v_mul_f32_e32 v130, v39, v39
	v_mul_f32_e32 v131, v41, v41
	v_fmac_f32_e32 v130, v38, v38
	v_fmac_f32_e32 v131, v40, v40
	v_add_f32_e32 v130, v130, v131
	v_add_f32_e32 v137, v130, v137
	v_mul_f32_e32 v130, v35, v35
	v_mul_f32_e32 v131, v37, v37
	v_fmac_f32_e32 v130, v34, v34
	v_fmac_f32_e32 v131, v36, v36
	v_add_f32_e32 v130, v130, v131
	v_add_f32_e32 v137, v130, v137
	ds_bpermute_b32 v145, v240, v137
	v_mul_f32_e32 v138, v31, v31
	v_mul_f32_e32 v131, v33, v33
	v_fmac_f32_e32 v138, v30, v30
	v_fmac_f32_e32 v131, v32, v32
	v_add_f32_e32 v138, v138, v131
	v_mul_f32_e32 v130, v27, v27
	v_mul_f32_e32 v131, v29, v29
	v_fmac_f32_e32 v130, v26, v26
	v_fmac_f32_e32 v131, v28, v28
	v_add_f32_e32 v130, v130, v131
	v_add_f32_e32 v138, v130, v138
	v_mul_f32_e32 v130, v23, v23
	v_mul_f32_e32 v131, v25, v25
	v_fmac_f32_e32 v130, v22, v22
	v_fmac_f32_e32 v131, v24, v24
	v_add_f32_e32 v130, v130, v131
	v_add_f32_e32 v138, v130, v138
	v_mul_f32_e32 v130, v19, v19
	v_mul_f32_e32 v131, v21, v21
	v_fmac_f32_e32 v130, v18, v18
	v_fmac_f32_e32 v131, v20, v20
	v_add_f32_e32 v130, v130, v131
	v_add_f32_e32 v138, v130, v138
	ds_bpermute_b32 v146, v240, v138
	v_mul_f32_e32 v139, v15, v15
	v_mul_f32_e32 v131, v17, v17
	v_fmac_f32_e32 v139, v14, v14
	v_fmac_f32_e32 v131, v16, v16
	v_add_f32_e32 v139, v139, v131
	v_mul_f32_e32 v130, v11, v11
	v_mul_f32_e32 v131, v13, v13
	v_fmac_f32_e32 v130, v10, v10
	v_fmac_f32_e32 v131, v12, v12
	v_add_f32_e32 v130, v130, v131
	v_add_f32_e32 v139, v130, v139
	v_mul_f32_e32 v130, v7, v7
	v_mul_f32_e32 v131, v9, v9
	v_fmac_f32_e32 v130, v6, v6
	v_fmac_f32_e32 v131, v8, v8
	v_add_f32_e32 v130, v130, v131
	v_add_f32_e32 v139, v130, v139
	v_mul_f32_e32 v130, v3, v3
	v_mul_f32_e32 v131, v5, v5
	v_fmac_f32_e32 v130, v2, v2
	v_fmac_f32_e32 v131, v4, v4
	v_add_f32_e32 v130, v130, v131
	v_add_f32_e32 v139, v130, v139
	ds_bpermute_b32 v147, v240, v139
	s_waitcnt lgkmcnt(0)
	v_add_f32_e32 v132, v132, v140
	ds_bpermute_b32 v140, v241, v132
	v_add_f32_e32 v133, v133, v141
	ds_bpermute_b32 v141, v241, v133
	v_add_f32_e32 v134, v134, v142
	ds_bpermute_b32 v142, v241, v134
	v_add_f32_e32 v135, v135, v143
	ds_bpermute_b32 v143, v241, v135
	v_add_f32_e32 v136, v136, v144
	ds_bpermute_b32 v144, v241, v136
	v_add_f32_e32 v137, v137, v145
	ds_bpermute_b32 v145, v241, v137
	v_add_f32_e32 v138, v138, v146
	ds_bpermute_b32 v146, v241, v138
	v_add_f32_e32 v139, v139, v147
	ds_bpermute_b32 v147, v241, v139
	s_and_saveexec_b64 s[30:31], s[6:7]
	s_cbranch_execz .Lpub1_skip
; __device__ __forceinline__ float shx(float v, int o, int lane) { return __builtin_bit_cast(float, __builtin_amdgcn_ds_bpermute((lane ^ o) << 2, __builtin_bit_cast(int, v))); }
; __device__ __forceinline__ void panel_ss_publish(const f32x4 (&v)[2][2][4][2], const Unit& u, int wr, int wc, int fr, int fq, PG8_LAS unsigned char* lds, int wid, int lane, float* slots, unsigned* cnt) {
;     ...
;             s += shx(s, 16, lane); s += shx(s, 32, lane);
;             if (fq == 0) P[(ai * HALF + wr * 64 + m * 16 + fr) * 4 + wc] = s; }
	s_waitcnt lgkmcnt(0)
	v_lshl_add_u32 v130, v238, 4, s4
	v_add_f32_e32 v132, v132, v140
	ds_write_b32 v130, v132
	v_add_f32_e32 v133, v133, v141
	ds_write_b32 v130, v133 offset:256
	v_add_f32_e32 v134, v134, v142
	ds_write_b32 v130, v134 offset:512
	v_add_f32_e32 v135, v135, v143
	ds_write_b32 v130, v135 offset:768
	v_add_f32_e32 v136, v136, v144
	ds_write_b32 v130, v136 offset:2048
	v_add_f32_e32 v137, v137, v145
	ds_write_b32 v130, v137 offset:2304
	v_add_f32_e32 v138, v138, v146
	ds_write_b32 v130, v138 offset:2560
	v_add_f32_e32 v139, v139, v147
	ds_write_b32 v130, v139 offset:2816
